# out-proj epilogue rewritten: residual loads/stores software-pipelined over 8 row-groups (3 in flight, SGPR-base addressing) so no load wait depends on a recent store
# speedup vs baseline: 1.0048x; 1.0048x over previous
.LBB0_128:
	v_readlane_b32 s4, v252, 26
	v_readlane_b32 s5, v252, 27
	s_and_b64 s[52:53], s[4:5], exec
	s_cselect_b32 s0, s61, s63
	s_cselect_b32 s37, s60, s62
	v_readlane_b32 s60, v253, 0
	v_readlane_b32 s4, v252, 19
	v_readlane_b32 s61, v253, 1
	s_add_u32 s52, s60, s37
	v_readlane_b32 s5, v252, 20
	s_addc_u32 s53, s61, s0
	s_mul_i32 s0, s4, 33
	s_mul_hi_i32 s37, s4, 33
	s_load_dwordx16 s[4:19], s[60:61], 0xf0
	s_add_u32 s0, s56, s0
	s_addc_u32 s37, s57, s37
	s_mulk_i32 s37, 0x6000
	s_mul_hi_u32 s39, s0, 0x6000
	s_add_i32 s39, s39, s37
	s_mulk_i32 s0, 0x6000
	s_waitcnt lgkmcnt(0)
	s_add_u32 s0, s6, s0
	s_addc_u32 s37, s7, s39
	s_lshl_b32 s56, s30, 8
	s_load_dwordx2 s[52:53], s[52:53], 0x0
	s_ashr_i32 s57, s56, 31
	s_lshl_b64 s[56:57], s[56:57], 2
	s_add_u32 s60, s0, s56
	s_addc_u32 s61, s37, s57
	s_lshl_b64 s[20:21], s[20:21], 2
	s_load_dwordx2 s[58:59], s[58:59], 0x0
	s_waitcnt lgkmcnt(0)
	s_add_u32 s0, s52, s20
	s_addc_u32 s30, s53, s21
	s_add_u32 s52, s0, s56
	s_addc_u32 s53, s30, s57
	s_add_u32 s0, s58, s20
	s_addc_u32 s21, s59, s21
	s_add_u32 s20, s0, s56
	s_addc_u32 s21, s21, s57
	s_mov_b64 s[56:57], -1
	s_andn2_b64 vcc, exec, s[54:55]
	v_add_u32_e32 v164, v176, v144
	s_add_u32 s8, s60, 0x2000
	s_addc_u32 s9, s61, 0
	global_load_dwordx4 v[128:131], v176, s[8:9]
	global_load_dwordx4 v[132:135], v176, s[8:9] offset:16
	global_load_dwordx4 v[166:169], v176, s[8:9] offset:128
	global_load_dwordx4 v[170:173], v176, s[8:9] offset:144
	s_add_u32 s10, s52, 0x0
	s_addc_u32 s11, s53, 0
	s_nop 0
	global_load_dwordx4 v[182:185], v164, s[10:11]
	global_load_dwordx4 v[186:189], v164, s[10:11] offset:16
	global_load_dwordx4 v[208:211], v164, s[10:11] offset:128
	global_load_dwordx4 v[212:215], v164, s[10:11] offset:144
	s_add_u32 s10, s52, 0x10000
	s_addc_u32 s11, s53, 0
	s_nop 0
	global_load_dwordx4 v[216:219], v164, s[10:11]
	global_load_dwordx4 v[220:223], v164, s[10:11] offset:16
	global_load_dwordx4 v[224:227], v164, s[10:11] offset:128
	global_load_dwordx4 v[228:231], v164, s[10:11] offset:144
	s_add_u32 s10, s52, 0x20000
	s_addc_u32 s11, s53, 0
	s_nop 0
	global_load_dwordx4 v[232:235], v164, s[10:11]
	global_load_dwordx4 v[236:239], v164, s[10:11] offset:16
	global_load_dwordx4 v[240:243], v164, s[10:11] offset:128
	global_load_dwordx4 v[244:247], v164, s[10:11] offset:144
	s_waitcnt vmcnt(8)
	v_pk_fma_f32 v[182:183], v[124:125], v[128:129], v[182:183]
	v_pk_fma_f32 v[184:185], v[126:127], v[130:131], v[184:185]
	v_pk_fma_f32 v[186:187], v[120:121], v[132:133], v[186:187]
	v_pk_fma_f32 v[188:189], v[122:123], v[134:135], v[188:189]
	v_pk_fma_f32 v[208:209], v[60:61], v[166:167], v[208:209]
	v_pk_fma_f32 v[210:211], v[62:63], v[168:169], v[210:211]
	v_pk_fma_f32 v[212:213], v[56:57], v[170:171], v[212:213]
	v_pk_fma_f32 v[214:215], v[58:59], v[172:173], v[214:215]
	s_add_u32 s12, s20, 0x0
	s_addc_u32 s13, s21, 0
	s_nop 0
	global_store_dwordx4 v164, v[182:185], s[12:13]
	global_store_dwordx4 v164, v[186:189], s[12:13] offset:16
	global_store_dwordx4 v164, v[208:211], s[12:13] offset:128
	global_store_dwordx4 v164, v[212:215], s[12:13] offset:144
	s_add_u32 s10, s52, 0x30000
	s_addc_u32 s11, s53, 0
	s_nop 0
	global_load_dwordx4 v[182:185], v164, s[10:11]
	global_load_dwordx4 v[186:189], v164, s[10:11] offset:16
	global_load_dwordx4 v[208:211], v164, s[10:11] offset:128
	global_load_dwordx4 v[212:215], v164, s[10:11] offset:144
	s_waitcnt vmcnt(12)
	v_pk_fma_f32 v[216:217], v[116:117], v[128:129], v[216:217]
	v_pk_fma_f32 v[218:219], v[118:119], v[130:131], v[218:219]
	v_pk_fma_f32 v[220:221], v[112:113], v[132:133], v[220:221]
	v_pk_fma_f32 v[222:223], v[114:115], v[134:135], v[222:223]
	v_pk_fma_f32 v[224:225], v[52:53], v[166:167], v[224:225]
	v_pk_fma_f32 v[226:227], v[54:55], v[168:169], v[226:227]
	v_pk_fma_f32 v[228:229], v[48:49], v[170:171], v[228:229]
	v_pk_fma_f32 v[230:231], v[50:51], v[172:173], v[230:231]
	s_add_u32 s12, s20, 0x10000
	s_addc_u32 s13, s21, 0
	s_nop 0
	global_store_dwordx4 v164, v[216:219], s[12:13]
	global_store_dwordx4 v164, v[220:223], s[12:13] offset:16
	global_store_dwordx4 v164, v[224:227], s[12:13] offset:128
	global_store_dwordx4 v164, v[228:231], s[12:13] offset:144
	s_add_u32 s10, s52, 0x80000
	s_addc_u32 s11, s53, 0
	s_nop 0
	global_load_dwordx4 v[216:219], v164, s[10:11]
	global_load_dwordx4 v[220:223], v164, s[10:11] offset:16
	global_load_dwordx4 v[224:227], v164, s[10:11] offset:128
	global_load_dwordx4 v[228:231], v164, s[10:11] offset:144
	s_waitcnt vmcnt(16)
	v_pk_fma_f32 v[232:233], v[108:109], v[128:129], v[232:233]
	v_pk_fma_f32 v[234:235], v[110:111], v[130:131], v[234:235]
	v_pk_fma_f32 v[236:237], v[104:105], v[132:133], v[236:237]
	v_pk_fma_f32 v[238:239], v[106:107], v[134:135], v[238:239]
	v_pk_fma_f32 v[240:241], v[44:45], v[166:167], v[240:241]
	v_pk_fma_f32 v[242:243], v[46:47], v[168:169], v[242:243]
	v_pk_fma_f32 v[244:245], v[40:41], v[170:171], v[244:245]
	v_pk_fma_f32 v[246:247], v[42:43], v[172:173], v[246:247]
	s_add_u32 s12, s20, 0x20000
	s_addc_u32 s13, s21, 0
	s_nop 0
	global_store_dwordx4 v164, v[232:235], s[12:13]
	global_store_dwordx4 v164, v[236:239], s[12:13] offset:16
	global_store_dwordx4 v164, v[240:243], s[12:13] offset:128
	global_store_dwordx4 v164, v[244:247], s[12:13] offset:144
	s_add_u32 s10, s52, 0x90000
	s_addc_u32 s11, s53, 0
	s_nop 0
	global_load_dwordx4 v[232:235], v164, s[10:11]
	global_load_dwordx4 v[236:239], v164, s[10:11] offset:16
	global_load_dwordx4 v[240:243], v164, s[10:11] offset:128
	global_load_dwordx4 v[244:247], v164, s[10:11] offset:144
	s_waitcnt vmcnt(16)
	v_pk_fma_f32 v[182:183], v[100:101], v[128:129], v[182:183]
	v_pk_fma_f32 v[184:185], v[102:103], v[130:131], v[184:185]
	v_pk_fma_f32 v[186:187], v[96:97], v[132:133], v[186:187]
	v_pk_fma_f32 v[188:189], v[98:99], v[134:135], v[188:189]
	v_pk_fma_f32 v[208:209], v[36:37], v[166:167], v[208:209]
	v_pk_fma_f32 v[210:211], v[38:39], v[168:169], v[210:211]
	v_pk_fma_f32 v[212:213], v[32:33], v[170:171], v[212:213]
	v_pk_fma_f32 v[214:215], v[34:35], v[172:173], v[214:215]
	s_add_u32 s12, s20, 0x30000
	s_addc_u32 s13, s21, 0
	s_nop 0
	global_store_dwordx4 v164, v[182:185], s[12:13]
	global_store_dwordx4 v164, v[186:189], s[12:13] offset:16
	global_store_dwordx4 v164, v[208:211], s[12:13] offset:128
	global_store_dwordx4 v164, v[212:215], s[12:13] offset:144
	s_add_u32 s10, s52, 0xa0000
	s_addc_u32 s11, s53, 0
	s_nop 0
	global_load_dwordx4 v[182:185], v164, s[10:11]
	global_load_dwordx4 v[186:189], v164, s[10:11] offset:16
	global_load_dwordx4 v[208:211], v164, s[10:11] offset:128
	global_load_dwordx4 v[212:215], v164, s[10:11] offset:144
	s_waitcnt vmcnt(16)
	v_pk_fma_f32 v[216:217], v[92:93], v[128:129], v[216:217]
	v_pk_fma_f32 v[218:219], v[94:95], v[130:131], v[218:219]
	v_pk_fma_f32 v[220:221], v[88:89], v[132:133], v[220:221]
	v_pk_fma_f32 v[222:223], v[90:91], v[134:135], v[222:223]
	v_pk_fma_f32 v[224:225], v[28:29], v[166:167], v[224:225]
	v_pk_fma_f32 v[226:227], v[30:31], v[168:169], v[226:227]
	v_pk_fma_f32 v[228:229], v[24:25], v[170:171], v[228:229]
	v_pk_fma_f32 v[230:231], v[26:27], v[172:173], v[230:231]
	s_add_u32 s12, s20, 0x80000
	s_addc_u32 s13, s21, 0
	s_nop 0
	global_store_dwordx4 v164, v[216:219], s[12:13]
	global_store_dwordx4 v164, v[220:223], s[12:13] offset:16
	global_store_dwordx4 v164, v[224:227], s[12:13] offset:128
	global_store_dwordx4 v164, v[228:231], s[12:13] offset:144
	s_add_u32 s10, s52, 0xb0000
	s_addc_u32 s11, s53, 0
	s_nop 0
	global_load_dwordx4 v[216:219], v164, s[10:11]
	global_load_dwordx4 v[220:223], v164, s[10:11] offset:16
	global_load_dwordx4 v[224:227], v164, s[10:11] offset:128
	global_load_dwordx4 v[228:231], v164, s[10:11] offset:144
	s_waitcnt vmcnt(16)
	v_pk_fma_f32 v[232:233], v[84:85], v[128:129], v[232:233]
	v_pk_fma_f32 v[234:235], v[86:87], v[130:131], v[234:235]
	v_pk_fma_f32 v[236:237], v[80:81], v[132:133], v[236:237]
	v_pk_fma_f32 v[238:239], v[82:83], v[134:135], v[238:239]
	v_pk_fma_f32 v[240:241], v[20:21], v[166:167], v[240:241]
	v_pk_fma_f32 v[242:243], v[22:23], v[168:169], v[242:243]
	v_pk_fma_f32 v[244:245], v[16:17], v[170:171], v[244:245]
	v_pk_fma_f32 v[246:247], v[18:19], v[172:173], v[246:247]
	s_add_u32 s12, s20, 0x90000
	s_addc_u32 s13, s21, 0
	s_nop 0
	global_store_dwordx4 v164, v[232:235], s[12:13]
	global_store_dwordx4 v164, v[236:239], s[12:13] offset:16
	global_store_dwordx4 v164, v[240:243], s[12:13] offset:128
	global_store_dwordx4 v164, v[244:247], s[12:13] offset:144
	s_waitcnt vmcnt(12)
	v_pk_fma_f32 v[182:183], v[76:77], v[128:129], v[182:183]
	v_pk_fma_f32 v[184:185], v[78:79], v[130:131], v[184:185]
	v_pk_fma_f32 v[186:187], v[72:73], v[132:133], v[186:187]
	v_pk_fma_f32 v[188:189], v[74:75], v[134:135], v[188:189]
	v_pk_fma_f32 v[208:209], v[12:13], v[166:167], v[208:209]
	v_pk_fma_f32 v[210:211], v[14:15], v[168:169], v[210:211]
	v_pk_fma_f32 v[212:213], v[8:9], v[170:171], v[212:213]
	v_pk_fma_f32 v[214:215], v[10:11], v[172:173], v[214:215]
	s_add_u32 s12, s20, 0xa0000
	s_addc_u32 s13, s21, 0
	s_nop 0
	global_store_dwordx4 v164, v[182:185], s[12:13]
	global_store_dwordx4 v164, v[186:189], s[12:13] offset:16
	global_store_dwordx4 v164, v[208:211], s[12:13] offset:128
	global_store_dwordx4 v164, v[212:215], s[12:13] offset:144
	s_waitcnt vmcnt(8)
	v_pk_fma_f32 v[216:217], v[68:69], v[128:129], v[216:217]
	v_pk_fma_f32 v[218:219], v[70:71], v[130:131], v[218:219]
	v_pk_fma_f32 v[220:221], v[64:65], v[132:133], v[220:221]
	v_pk_fma_f32 v[222:223], v[66:67], v[134:135], v[222:223]
	v_pk_fma_f32 v[224:225], v[4:5], v[166:167], v[224:225]
	v_pk_fma_f32 v[226:227], v[6:7], v[168:169], v[226:227]
	v_pk_fma_f32 v[228:229], v[0:1], v[170:171], v[228:229]
	v_pk_fma_f32 v[230:231], v[2:3], v[172:173], v[230:231]
	s_add_u32 s12, s20, 0xb0000
	s_addc_u32 s13, s21, 0
	s_nop 0
	global_store_dwordx4 v164, v[216:219], s[12:13]
	global_store_dwordx4 v164, v[220:223], s[12:13] offset:16
	global_store_dwordx4 v164, v[224:227], s[12:13] offset:128
	global_store_dwordx4 v164, v[228:231], s[12:13] offset:144
	s_cbranch_vccnz .LBB0_98
	v_readlane_b32 s4, v252, 32
	v_readlane_b32 s5, v252, 33
	s_andn2_b64 vcc, exec, s[4:5]
	s_cbranch_vccnz .LBB0_97
	s_barrier
	s_branch .LBB0_97
